# v47 + GEMM phase prologue: K-tile 1 LDS-DMA loads issued before the first wait (vmcnt 8 then 6), artifact vmcnt(0) in the down prologue dropped
# speedup vs baseline: 1.0068x; 1.0025x over previous
.LBB0_120:
	v_and_b32_e32 v150, 15, v10
	v_and_b32_e32 v151, 63, v10
	v_bfe_u32 v152, v10, 4, 2
	v_and_b32_e32 v17, 48, v10
	v_lshlrev_b32_e32 v10, 2, v10
	s_and_b32 s5, s12, 3
	s_lshl_b32 s7, s11, 13
	v_lshl_or_b32 v17, v150, 6, v17
	v_and_b32_e32 v10, 32, v10
	s_add_i32 m0, s16, 0x18000
	v_lshl_add_u64 v[8:9], v[8:9], 0, s[88:89]
	s_lshl_b32 s56, s11, 6
	v_bitop3_b32 v18, v17, s7, v10 bitop3:0xde
	s_lshl_b32 s33, s5, 5
	s_lshl_b32 s7, s5, 12
	global_load_lds_dwordx4 v[8:9], off
	v_lshl_add_u64 v[6:7], v[6:7], 0, s[88:89]
	s_add_i32 m0, s16, 0x1a000
	s_add_i32 s52, s16, 0x8000
	s_add_i32 s90, s16, 0xa000
	global_load_lds_dwordx4 v[6:7], off
	v_lshl_add_u64 v[2:3], v[2:3], 0, s[88:89]
	s_mov_b32 m0, s52
	s_add_u32 s18, s8, 0x100080
	global_load_lds_dwordx4 v[2:3], off
	v_lshl_add_u64 v[2:3], v[4:5], 0, s[88:89]
	s_mov_b32 m0, s90
	s_addc_u32 s19, s9, 0
	global_load_lds_dwordx4 v[2:3], off
	s_add_i32 m0, s16, 0x1c000
	v_lshl_add_u64 v[2:3], s[18:19], 0, v[0:1]
	global_load_lds_dwordx4 v[2:3], off
	v_lshl_add_u64 v[2:3], s[18:19], 0, v[134:135]
	s_add_i32 m0, s16, 0x1e000
	v_bitop3_b32 v153, v17, s7, v10 bitop3:0xde
	global_load_lds_dwordx4 v[2:3], off
	s_waitcnt vmcnt(8)
	s_barrier
	s_lshl_b32 s7, s12, 4
	v_lshlrev_b32_e32 v2, 16, v11
	s_and_b32 s18, s7, 0xffffffc0
	v_and_b32_e32 v2, 0xfffe0000, v2
	s_or_b32 s91, s5, 0xffffffb8
	s_ashr_i32 s19, s18, 31
	s_lshl_b32 s7, s12, 9
	v_lshl_add_u32 v2, v12, 13, v2
	v_and_b32_e32 v3, 1, v11
	s_cmpk_lt_u32 s10, 0x100
	v_lshl_or_b32 v2, v3, 6, v2
	s_cselect_b64 s[94:95], -1, 0
	s_lshl_b32 s12, s11, 11
	s_lshl_b32 s5, s5, 9
	s_lshl_b64 s[10:11], s[18:19], 2
	v_readlane_b32 s13, v254, 7
	v_lshl_add_u32 v136, v13, 1, v2
	v_lshlrev_b32_e32 v2, 16, v14
	s_add_u32 s54, s13, s10
	v_readlane_b32 s10, v254, 8
	v_and_b32_e32 v2, 0xfffe0000, v2
	s_waitcnt vmcnt(6)
	s_addc_u32 s60, s10, s11
	s_add_i32 s10, s12, 0
	v_lshl_add_u32 v2, v15, 13, v2
	v_and_b32_e32 v3, 1, v14
	s_add_i32 s20, s10, s5
	v_lshl_or_b32 v2, v3, 6, v2
	s_add_i32 s22, s7, 0
	s_add_i32 s20, s20, 0x20400
	v_mov_b32_e32 v137, v1
	v_lshl_add_u32 v138, v16, 1, v2
	v_mov_b32_e32 v139, v1
	s_mov_b32 s21, 0
	s_add_i32 s23, s22, 0x20500
	v_add_u32_e32 v154, 0, v18
	s_barrier
	s_branch .LBB0_123

.LBB0_719:
	v_readlane_b32 s10, v253, 47
	s_add_u32 s8, s4, 0x100080
	v_mov_b32_e32 v135, v1
	v_readlane_b32 s11, v253, 48
	s_addc_u32 s9, s5, 0
	s_add_i32 m0, s23, 0x18000
	v_lshl_add_u64 v[2:3], v[2:3], 0, s[88:89]
	v_lshl_add_u64 v[14:15], s[10:11], 0, v[134:135]
	v_mov_b32_e32 v137, v1
	global_load_lds_dwordx4 v[2:3], off
	v_lshl_add_u64 v[2:3], v[4:5], 0, s[88:89]
	s_add_i32 m0, s23, 0x1a000
	s_add_i32 s29, s23, 0x8000
	v_lshl_add_u64 v[16:17], s[10:11], 0, v[136:137]
	global_load_lds_dwordx4 v[2:3], off
	v_lshl_add_u64 v[2:3], v[14:15], 0, s[88:89]
	s_mov_b32 m0, s29
	s_add_i32 s30, s23, 0xa000
	global_load_lds_dwordx4 v[2:3], off
	v_lshl_add_u64 v[2:3], v[16:17], 0, s[88:89]
	s_mov_b32 m0, s30
	v_bfe_u32 v151, v10, 4, 2
	global_load_lds_dwordx4 v[2:3], off
	s_add_i32 m0, s23, 0x1c000
	v_lshl_add_u64 v[2:3], s[8:9], 0, v[0:1]
	global_load_lds_dwordx4 v[2:3], off
	v_lshl_add_u64 v[2:3], s[8:9], 0, v[138:139]
	s_add_i32 m0, s23, 0x1e000
	s_lshl_b32 s1, s1, 5
	global_load_lds_dwordx4 v[2:3], off
	s_waitcnt vmcnt(8)
	s_barrier
	v_lshlrev_b32_e32 v2, 16, v6
	v_and_b32_e32 v2, 0xfffe0000, v2
	v_and_b32_e32 v150, 15, v10
	v_lshlrev_b32_e32 v13, 4, v151
	v_lshlrev_b32_e32 v10, 2, v10
	s_and_b32 s28, s1, 0x60
	v_lshl_add_u32 v2, v7, 13, v2
	v_and_b32_e32 v3, 1, v6
	s_lshl_b32 s27, s2, 6
	v_lshl_or_b32 v13, v150, 6, v13
	s_lshl_b32 s2, s2, 13
	v_and_b32_e32 v10, 32, v10
	s_lshl_b32 s1, s28, 7
	v_lshl_or_b32 v2, v3, 6, v2
	v_bitop3_b32 v152, v13, s1, v10 bitop3:0xde
	s_cmpk_lt_u32 s0, 0x100
	v_lshl_add_u32 v2, v8, 1, v2
	v_mov_b32_e32 v3, v1
	s_mov_b64 s[0:1], 0x100080
	v_lshl_add_u64 v[140:141], v[2:3], 0, s[0:1]
	v_lshlrev_b32_e32 v2, 16, v9
	v_and_b32_e32 v2, 0xfffe0000, v2
	v_lshl_add_u32 v2, v11, 13, v2
	v_and_b32_e32 v3, 1, v9
	v_lshl_or_b32 v2, v3, 6, v2
	s_waitcnt vmcnt(6)
	v_lshl_add_u32 v2, v12, 1, v2
	v_mov_b32_e32 v3, v1
	v_bitop3_b32 v18, v13, s2, v10 bitop3:0xde
	v_lshl_add_u64 v[142:143], v[2:3], 0, s[0:1]
	v_mov_b32_e32 v2, 0
	v_readlane_b32 s0, v253, 57
	s_cselect_b64 s[8:9], -1, 0
	s_mov_b32 s33, 0
	s_mov_b32 s31, 64
	s_mov_b32 s86, -1
	v_add_u32_e32 v153, 0, v18
	v_readlane_b32 s52, v253, 42
	s_mov_b32 s53, s0
	v_mov_b32_e32 v3, v2
	v_mov_b32_e32 v4, v2
	v_mov_b32_e32 v5, v2
	v_mov_b32_e32 v6, v2
	v_mov_b32_e32 v7, v2
	v_mov_b32_e32 v8, v2
	v_mov_b32_e32 v9, v2
	v_mov_b32_e32 v10, v2
	v_mov_b32_e32 v11, v2
	v_mov_b32_e32 v12, v2
	v_mov_b32_e32 v13, v2
	v_mov_b32_e32 v14, v2
	v_mov_b32_e32 v15, v2
	v_mov_b32_e32 v16, v2
	v_mov_b32_e32 v17, v2
	v_mov_b32_e32 v18, v2
	v_mov_b32_e32 v19, v2
	v_mov_b32_e32 v20, v2
	v_mov_b32_e32 v21, v2
	v_mov_b32_e32 v22, v2
	v_mov_b32_e32 v23, v2
	v_mov_b32_e32 v24, v2
	v_mov_b32_e32 v25, v2
	v_mov_b32_e32 v26, v2
	v_mov_b32_e32 v27, v2
	v_mov_b32_e32 v28, v2
	v_mov_b32_e32 v29, v2
	v_mov_b32_e32 v30, v2
	v_mov_b32_e32 v31, v2
	v_mov_b32_e32 v32, v2
	v_mov_b32_e32 v33, v2
	v_mov_b32_e32 v34, v2
	v_mov_b32_e32 v35, v2
	v_mov_b32_e32 v36, v2
	v_mov_b32_e32 v37, v2
	v_mov_b32_e32 v38, v2
	v_mov_b32_e32 v39, v2
	v_mov_b32_e32 v40, v2
	v_mov_b32_e32 v41, v2
	v_mov_b32_e32 v42, v2
	v_mov_b32_e32 v43, v2
	v_mov_b32_e32 v44, v2
	v_mov_b32_e32 v45, v2
	v_mov_b32_e32 v46, v2
	v_mov_b32_e32 v47, v2
	v_mov_b32_e32 v48, v2
	v_mov_b32_e32 v49, v2
	v_mov_b32_e32 v50, v2
	v_mov_b32_e32 v51, v2
	v_mov_b32_e32 v52, v2
	v_mov_b32_e32 v53, v2
	v_mov_b32_e32 v54, v2
	v_mov_b32_e32 v55, v2
	v_mov_b32_e32 v56, v2
	v_mov_b32_e32 v57, v2
	v_mov_b32_e32 v58, v2
	v_mov_b32_e32 v59, v2
	v_mov_b32_e32 v60, v2
	v_mov_b32_e32 v61, v2
	v_mov_b32_e32 v62, v2
	v_mov_b32_e32 v63, v2
	v_mov_b32_e32 v64, v2
	v_mov_b32_e32 v65, v2
	v_mov_b32_e32 v66, v2
	v_mov_b32_e32 v67, v2
	v_mov_b32_e32 v68, v2
	v_mov_b32_e32 v69, v2
	v_mov_b32_e32 v70, v2
	v_mov_b32_e32 v71, v2
	v_mov_b32_e32 v72, v2
	v_mov_b32_e32 v73, v2
	v_mov_b32_e32 v74, v2
	v_mov_b32_e32 v75, v2
	v_mov_b32_e32 v76, v2
	v_mov_b32_e32 v77, v2
	v_mov_b32_e32 v78, v2
	v_mov_b32_e32 v79, v2
	v_mov_b32_e32 v80, v2
	v_mov_b32_e32 v81, v2
	v_mov_b32_e32 v82, v2
	v_mov_b32_e32 v83, v2
	v_mov_b32_e32 v84, v2
	v_mov_b32_e32 v85, v2
	v_mov_b32_e32 v86, v2
	v_mov_b32_e32 v87, v2
	v_mov_b32_e32 v88, v2
	v_mov_b32_e32 v89, v2
	v_mov_b32_e32 v90, v2
	v_mov_b32_e32 v91, v2
	v_mov_b32_e32 v92, v2
	v_mov_b32_e32 v93, v2
	v_mov_b32_e32 v94, v2
	v_mov_b32_e32 v95, v2
	v_mov_b32_e32 v96, v2
	v_mov_b32_e32 v97, v2
	v_mov_b32_e32 v98, v2
	v_mov_b32_e32 v99, v2
	v_mov_b32_e32 v100, v2
	v_mov_b32_e32 v101, v2
	v_mov_b32_e32 v102, v2
	v_mov_b32_e32 v103, v2
	v_mov_b32_e32 v104, v2
	v_mov_b32_e32 v105, v2
	v_mov_b32_e32 v106, v2
	v_mov_b32_e32 v107, v2
	v_mov_b32_e32 v108, v2
	v_mov_b32_e32 v109, v2
	v_mov_b32_e32 v110, v2
	v_mov_b32_e32 v111, v2
	v_mov_b32_e32 v112, v2
	v_mov_b32_e32 v113, v2
	v_mov_b32_e32 v114, v2
	v_mov_b32_e32 v115, v2
	v_mov_b32_e32 v116, v2
	v_mov_b32_e32 v117, v2
	v_mov_b32_e32 v118, v2
	v_mov_b32_e32 v119, v2
	v_mov_b32_e32 v120, v2
	v_mov_b32_e32 v121, v2
	v_mov_b32_e32 v122, v2
	v_mov_b32_e32 v123, v2
	v_mov_b32_e32 v124, v2
	v_mov_b32_e32 v125, v2
	v_mov_b32_e32 v126, v2
	v_mov_b32_e32 v127, v2
	v_mov_b32_e32 v128, v2
	v_mov_b32_e32 v129, v2
	s_barrier
	v_readlane_b32 s1, v253, 58
	s_branch .LBB0_722

.LBB0_872:
	v_and_b32_e32 v218, 15, v0
	v_and_b32_e32 v219, 63, v0
	v_bfe_u32 v220, v0, 4, 2
	v_and_b32_e32 v20, 48, v0
	v_lshlrev_b32_e32 v0, 2, v0
	s_and_b32 s3, s7, 3
	s_lshl_b32 s24, s30, 13
	v_lshl_or_b32 v20, v218, 6, v20
	v_and_b32_e32 v0, 32, v0
	s_add_i32 m0, s9, 0x18000
	v_lshl_add_u64 v[8:9], v[8:9], 0, s[88:89]
	s_lshl_b32 s56, s30, 6
	v_bitop3_b32 v21, v20, s24, v0 bitop3:0xde
	s_lshl_b32 s57, s3, 5
	s_lshl_b32 s24, s3, 12
	global_load_lds_dwordx4 v[8:9], off
	v_lshl_add_u64 v[6:7], v[6:7], 0, s[88:89]
	s_add_i32 m0, s9, 0x1a000
	s_add_i32 s63, s9, 0x8000
	s_add_i32 s90, s9, 0xa000
	v_bitop3_b32 v221, v20, s24, v0 bitop3:0xde
	global_load_lds_dwordx4 v[6:7], off
	v_lshl_add_u64 v[2:3], v[2:3], 0, s[88:89]
	s_mov_b32 m0, s63
	s_add_u32 s24, s4, 0x100080
	global_load_lds_dwordx4 v[2:3], off
	v_lshl_add_u64 v[2:3], v[4:5], 0, s[88:89]
	s_mov_b32 m0, s90
	s_addc_u32 s25, s5, 0
	global_load_lds_dwordx4 v[2:3], off
	s_add_i32 m0, s9, 0x1c000
	v_lshl_add_u64 v[2:3], s[24:25], 0, v[182:183]
	global_load_lds_dwordx4 v[2:3], off
	v_lshl_add_u64 v[2:3], s[24:25], 0, v[186:187]
	s_add_i32 m0, s9, 0x1e000
	s_lshl_b32 s24, s7, 5
	global_load_lds_dwordx4 v[2:3], off
	s_waitcnt vmcnt(8)
	s_barrier
	s_lshl_b32 s7, s7, 4
	s_and_b32 s91, s24, 0x60
	s_and_b32 s24, s7, 0xffffffc0
	s_ashr_i32 s25, s24, 31
	s_cmpk_lt_u32 s6, 0x100
	s_cselect_b64 s[94:95], -1, 0
	s_lshl_b32 s34, s30, 12
	s_lshl_b32 s3, s3, 10
	s_lshl_b64 s[6:7], s[24:25], 2
	v_readlane_b32 s24, v254, 7
	v_and_b32_e32 v2, 1, v10
	s_add_u32 s24, s24, s6
	v_readlane_b32 s6, v254, 8
	v_add3_u32 v0, v12, v13, v15
	v_lshlrev_b32_e32 v2, 6, v2
	s_addc_u32 s25, s6, s7
	s_add_i32 s6, s34, 0
	v_lshl_or_b32 v0, v0, 13, v2
	s_add_i32 s66, s6, s3
	v_lshl_add_u32 v0, v11, 1, v0
	s_mov_b64 s[6:7], 0x100080
	v_and_b32_e32 v2, 1, v14
	v_lshl_add_u64 v[188:189], v[0:1], 0, s[6:7]
	v_add3_u32 v0, v17, v18, v19
	v_lshlrev_b32_e32 v2, 6, v2
	s_waitcnt vmcnt(6)
	v_lshl_or_b32 v0, v0, 13, v2
	v_lshl_add_u32 v0, v16, 1, v0
	s_add_i32 s66, s66, 0x20400
	v_lshl_add_u64 v[190:191], v[0:1], 0, s[6:7]
	s_mov_b32 s67, 0
	v_add_u32_e32 v222, 0, v21
	s_barrier
	s_branch .LBB0_875

.LBB0_1154:
	v_readlane_b32 s10, v253, 59
	s_add_u32 s8, s4, 0x2b0080
	v_mov_b32_e32 v135, v1
	v_readlane_b32 s11, v253, 60
	s_addc_u32 s9, s5, 0
	s_add_i32 m0, s23, 0x18000
	v_lshl_add_u64 v[2:3], v[2:3], 0, s[88:89]
	v_lshl_add_u64 v[16:17], s[10:11], 0, v[134:135]
	v_mov_b32_e32 v137, v1
	global_load_lds_dwordx4 v[2:3], off
	v_lshl_add_u64 v[2:3], v[4:5], 0, s[88:89]
	s_add_i32 m0, s23, 0x1a000
	s_add_i32 s29, s23, 0x8000
	s_nop 0
	v_lshl_add_u64 v[18:19], s[10:11], 0, v[136:137]
	global_load_lds_dwordx4 v[2:3], off
	v_lshl_add_u64 v[2:3], v[16:17], 0, s[88:89]
	s_mov_b32 m0, s29
	s_add_i32 s30, s23, 0xa000
	global_load_lds_dwordx4 v[2:3], off
	v_lshl_add_u64 v[2:3], v[18:19], 0, s[88:89]
	s_mov_b32 m0, s30
	v_bfe_u32 v151, v11, 4, 2
	global_load_lds_dwordx4 v[2:3], off
	s_add_i32 m0, s23, 0x1c000
	v_lshl_add_u64 v[2:3], s[8:9], 0, v[0:1]
	global_load_lds_dwordx4 v[2:3], off
	v_lshl_add_u64 v[2:3], s[8:9], 0, v[138:139]
	s_add_i32 m0, s23, 0x1e000
	v_and_b32_e32 v150, 15, v11
	global_load_lds_dwordx4 v[2:3], off
	s_waitcnt vmcnt(8)
	s_barrier
	v_lshlrev_b32_e32 v15, 4, v151
	v_lshlrev_b32_e32 v11, 2, v11
	s_lshl_b32 s27, s0, 6
	v_lshl_or_b32 v15, v150, 6, v15
	s_lshl_b32 s0, s0, 13
	v_and_b32_e32 v11, 32, v11
	v_bitop3_b32 v20, v15, s0, v11 bitop3:0xde
	s_lshl_b32 s0, s3, 5
	s_and_b32 s28, s0, 0x60
	s_lshl_b32 s0, s28, 7
	s_cmpk_lt_u32 s2, 0x100
	s_movk_i32 s2, 0x2b00
	v_lshrrev_b32_e32 v3, 1, v6
	v_mul_lo_u32 v2, v8, s2
	s_mov_b32 s3, 0x2b000
	v_bitop3_b32 v152, v15, s0, v11 bitop3:0xde
	v_mad_u64_u32 v[2:3], s[0:1], v3, s3, v[2:3]
	v_or_b32_e32 v2, v2, v7
	v_add_lshl_u32 v2, v2, v9, 1
	v_mov_b32_e32 v3, v1
	s_mov_b64 s[12:13], 0x2b0080
	v_lshl_add_u64 v[140:141], v[2:3], 0, s[12:13]
	v_lshrrev_b32_e32 v3, 1, v10
	v_mul_lo_u32 v2, v13, s2
	v_mad_u64_u32 v[2:3], s[0:1], v3, s3, v[2:3]
	v_or_b32_e32 v2, v2, v12
	s_waitcnt vmcnt(6)
	v_add_lshl_u32 v2, v2, v14, 1
	v_mov_b32_e32 v3, v1
	v_lshl_add_u64 v[142:143], v[2:3], 0, s[12:13]
	v_mov_b32_e32 v2, 0
	v_readlane_b32 s0, v253, 57
	s_cselect_b64 s[8:9], -1, 0
	s_mov_b32 s33, 0
	s_movk_i32 s31, 0xac
	s_mov_b32 s86, -1
	v_add_u32_e32 v153, 0, v20
	v_readlane_b32 s52, v253, 42
	s_mov_b32 s53, s0
	v_mov_b32_e32 v3, v2
	v_mov_b32_e32 v4, v2
	v_mov_b32_e32 v5, v2
	v_mov_b32_e32 v6, v2
	v_mov_b32_e32 v7, v2
	v_mov_b32_e32 v8, v2
	v_mov_b32_e32 v9, v2
	v_mov_b32_e32 v10, v2
	v_mov_b32_e32 v11, v2
	v_mov_b32_e32 v12, v2
	v_mov_b32_e32 v13, v2
	v_mov_b32_e32 v14, v2
	v_mov_b32_e32 v15, v2
	v_mov_b32_e32 v16, v2
	v_mov_b32_e32 v17, v2
	v_mov_b32_e32 v18, v2
	v_mov_b32_e32 v19, v2
	v_mov_b32_e32 v20, v2
	v_mov_b32_e32 v21, v2
	v_mov_b32_e32 v22, v2
	v_mov_b32_e32 v23, v2
	v_mov_b32_e32 v24, v2
	v_mov_b32_e32 v25, v2
	v_mov_b32_e32 v26, v2
	v_mov_b32_e32 v27, v2
	v_mov_b32_e32 v28, v2
	v_mov_b32_e32 v29, v2
	v_mov_b32_e32 v30, v2
	v_mov_b32_e32 v31, v2
	v_mov_b32_e32 v32, v2
	v_mov_b32_e32 v33, v2
	v_mov_b32_e32 v34, v2
	v_mov_b32_e32 v35, v2
	v_mov_b32_e32 v36, v2
	v_mov_b32_e32 v37, v2
	v_mov_b32_e32 v38, v2
	v_mov_b32_e32 v39, v2
	v_mov_b32_e32 v40, v2
	v_mov_b32_e32 v41, v2
	v_mov_b32_e32 v42, v2
	v_mov_b32_e32 v43, v2
	v_mov_b32_e32 v44, v2
	v_mov_b32_e32 v45, v2
	v_mov_b32_e32 v46, v2
	v_mov_b32_e32 v47, v2
	v_mov_b32_e32 v48, v2
	v_mov_b32_e32 v49, v2
	v_mov_b32_e32 v50, v2
	v_mov_b32_e32 v51, v2
	v_mov_b32_e32 v52, v2
	v_mov_b32_e32 v53, v2
	v_mov_b32_e32 v54, v2
	v_mov_b32_e32 v55, v2
	v_mov_b32_e32 v56, v2
	v_mov_b32_e32 v57, v2
	v_mov_b32_e32 v58, v2
	v_mov_b32_e32 v59, v2
	v_mov_b32_e32 v60, v2
	v_mov_b32_e32 v61, v2
	v_mov_b32_e32 v62, v2
	v_mov_b32_e32 v63, v2
	v_mov_b32_e32 v64, v2
	v_mov_b32_e32 v65, v2
	v_mov_b32_e32 v66, v2
	v_mov_b32_e32 v67, v2
	v_mov_b32_e32 v68, v2
	v_mov_b32_e32 v69, v2
	v_mov_b32_e32 v70, v2
	v_mov_b32_e32 v71, v2
	v_mov_b32_e32 v72, v2
	v_mov_b32_e32 v73, v2
	v_mov_b32_e32 v74, v2
	v_mov_b32_e32 v75, v2
	v_mov_b32_e32 v76, v2
	v_mov_b32_e32 v77, v2
	v_mov_b32_e32 v78, v2
	v_mov_b32_e32 v79, v2
	v_mov_b32_e32 v80, v2
	v_mov_b32_e32 v81, v2
	v_mov_b32_e32 v82, v2
	v_mov_b32_e32 v83, v2
	v_mov_b32_e32 v84, v2
	v_mov_b32_e32 v85, v2
	v_mov_b32_e32 v86, v2
	v_mov_b32_e32 v87, v2
	v_mov_b32_e32 v88, v2
	v_mov_b32_e32 v89, v2
	v_mov_b32_e32 v90, v2
	v_mov_b32_e32 v91, v2
	v_mov_b32_e32 v92, v2
	v_mov_b32_e32 v93, v2
	v_mov_b32_e32 v94, v2
	v_mov_b32_e32 v95, v2
	v_mov_b32_e32 v96, v2
	v_mov_b32_e32 v97, v2
	v_mov_b32_e32 v98, v2
	v_mov_b32_e32 v99, v2
	v_mov_b32_e32 v100, v2
	v_mov_b32_e32 v101, v2
	v_mov_b32_e32 v102, v2
	v_mov_b32_e32 v103, v2
	v_mov_b32_e32 v104, v2
	v_mov_b32_e32 v105, v2
	v_mov_b32_e32 v106, v2
	v_mov_b32_e32 v107, v2
	v_mov_b32_e32 v108, v2
	v_mov_b32_e32 v109, v2
	v_mov_b32_e32 v110, v2
	v_mov_b32_e32 v111, v2
	v_mov_b32_e32 v112, v2
	v_mov_b32_e32 v113, v2
	v_mov_b32_e32 v114, v2
	v_mov_b32_e32 v115, v2
	v_mov_b32_e32 v116, v2
	v_mov_b32_e32 v117, v2
	v_mov_b32_e32 v118, v2
	v_mov_b32_e32 v119, v2
	v_mov_b32_e32 v120, v2
	v_mov_b32_e32 v121, v2
	v_mov_b32_e32 v122, v2
	v_mov_b32_e32 v123, v2
	v_mov_b32_e32 v124, v2
	v_mov_b32_e32 v125, v2
	v_mov_b32_e32 v126, v2
	v_mov_b32_e32 v127, v2
	v_mov_b32_e32 v128, v2
	v_mov_b32_e32 v129, v2
	s_barrier
	v_readlane_b32 s1, v253, 58
	s_branch .LBB0_1157
